# NSA selected loop: K fragment ds_reads issued right after the step barrier, before DMA issue and mask computation
# baseline (speedup 1.0000x reference)
; template <bool FX>
; DI void nsa_tile(const Params& p, int b, int g, int tile, bf16_t* lds, const float CL) {
;     ...
;       for (int s = 0; s <= cur; ++s) {
;         __syncthreads();
;         tile64_sstore(tid, Ks, rk0, rk1);
;         tile64_sstore(tid, Vs, rv0, rv1);
;         __syncthreads();
;         if (s < cur) {
;           tile64_gload(tid, rk0, rk1, kb + (size_t)(s + 1) * 64 * ZS, ZS);
;           tile64_gload(tid, rv0, rv1, vsT + (s + 1) * 64, TS);
.LBB0_668:
	s_add_i32 s68, s68, 1
	s_waitcnt vmcnt(0)
	s_barrier
	ds_read_b128 v[220:223], v188
	ds_read_b128 v[224:227], v188 offset:2048
	ds_read_b128 v[228:231], v188 offset:4096
	ds_read_b128 v[232:235], v189
	ds_read_b128 v[236:239], v190
	ds_read_b128 v[240:243], v190 offset:2048
	ds_read_b128 v[244:247], v190 offset:4096
	ds_read_b128 v[198:201], v191
	s_cmp_ge_u32 s68, s25
	s_cbranch_scc1 .LBB0_670
	s_lshl_b64 s[2:3], s[28:29], 1
	s_add_u32 s2, s12, s2
	s_addc_u32 s3, s13, s3
	v_lshl_add_u64 v[66:67], v[138:139], 1, s[2:3]
	v_lshl_add_u64 v[68:69], v[142:143], 1, s[2:3]
	v_lshl_add_u64 v[66:67], v[66:67], 0, v[202:203]
	v_lshl_add_u64 v[70:71], v[68:69], 0, v[202:203]
	s_mov_b32 m0, s76
	s_nop 0
	global_load_lds_dwordx4 v[158:159], off
	s_add_u32 m0, s76, 0x1000
	s_nop 0
	global_load_lds_dwordx4 v[160:161], off
	s_add_u32 m0, s76, 0x2000
	s_nop 0
	global_load_lds_dwordx4 v[66:67], off
	s_add_u32 m0, s76, 0x3000
	s_nop 0
	global_load_lds_dwordx4 v[70:71], off
	s_xor_b32 s76, s76, 0xc000
; template <int MODE, bool FX>
; DI void attn_compute(const int lane, const bf16_t* Ks, const bf16_t* Vs, const bf16x8 (&qf)[2][2], AttnSt& st, const float (&invl)[2],
;                      int lo, int hi, float (&impA)[4], float (&impE)[4], const float CL) {
;     ...
; #pragma unroll
;   for (int hh = 0; hh < 2; ++hh) {
;     if (FX) {
;       constexpr float L2E = 1.4426950408889634f;
;       const float il = (MODE == 1) ? invl[hh] : 1.f;
;       float rs = 0.f;
; #pragma unroll
;       for (int kt = 0; kt < 4; ++kt) {
;         float a = 0.f;
; #pragma unroll
;         for (int j = 0; j < 4; ++j) {
;           const int kl = kt * 16 + quad * 4 + j;
;           const bool v = (kl >= lo) && (kl <= hi);
;           float pv = v ? __builtin_amdgcn_exp2f(fmaf(S[kt][hh][j], L2E, -CL)) : 0.f;
;           if (MODE == 1) pv *= il;
;           S[kt][hh][j] = pv;
;           a += pv;
;         }
;         rs += a;
;         if (MODE == 1) {
;           impA[kt] += a;
;           impE[kt] += S[kt][hh][3];
;         }
;       }
;       if (MODE != 1 && !(FX && MODE == 2)) st.l[hh] += rs;
;       if (MODE != 0) {
; #pragma unroll
;         for (int c = 0; c < 2; ++c)
;           pf[hh][c] = mk8(pack2(S[2 * c][hh][0], S[2 * c][hh][1]), pack2(S[2 * c][hh][2], S[2 * c][hh][3]),
;                           pack2(S[2 * c + 1][hh][0], S[2 * c + 1][hh][1]), pack2(S[2 * c + 1][hh][2], S[2 * c + 1][hh][3]));
; template <bool FX>
; DI void nsa_tile(const Params& p, int b, int g, int tile, bf16_t* lds, const float CL) {
;     ...
;         uint32_t wsel = (s < 32) ? sw0 : (s < 64) ? sw1 : (s < 96) ? sw2 : sw3;
;         bool sel = (wsel >> (s & 31)) & 1u;
;         int hi = sel ? (tok - s * 64) : -1;
;         if (__any(hi >= 0)) attn_compute<2, FX>(lane, Ks, Vs, qf, st, invl, 0, hi, dA, dE, CL);
.LBB0_670:
	s_cmp_lt_u32 s68, 32
	s_cselect_b64 vcc, -1, 0
	s_cmp_lt_u32 s68, 64
	s_cselect_b64 s[2:3], -1, 0
	s_cmpk_lt_u32 s68, 0x60
	s_cselect_b64 s[4:5], -1, 0
	v_cndmask_b32_e64 v74, v183, v182, s[4:5]
	v_cndmask_b32_e64 v74, v74, v181, s[2:3]
	v_cndmask_b32_e32 v74, v74, v180, vcc
	v_lshrrev_b32_e32 v74, s68, v74
	v_and_b32_e32 v74, 1, v74
	v_cmp_eq_u32_e32 vcc, 1, v74
	s_nop 1
	v_cndmask_b32_e32 v215, -1, v187, vcc
	v_cmp_lt_i32_e32 vcc, -1, v215
	s_cbranch_vccz .LBB0_667
	v_cmp_lt_u32_e32 vcc, 62, v215
	s_mov_b64 s[2:3], -1
	s_cmp_eq_u64 vcc, exec
	s_cbranch_scc1 .Lnsa_fast
	s_waitcnt lgkmcnt(7)
	v_mfma_f32_16x16x32_bf16 v[98:101], v[220:223], v[2:5], 0
	v_mfma_f32_16x16x32_bf16 v[90:93], v[220:223], v[10:13], 0
	s_waitcnt lgkmcnt(6)
	v_mfma_f32_16x16x32_bf16 v[106:109], v[224:227], v[2:5], 0
	v_mfma_f32_16x16x32_bf16 v[94:97], v[224:227], v[10:13], 0
	s_waitcnt lgkmcnt(5)
	v_mfma_f32_16x16x32_bf16 v[102:105], v[228:231], v[2:5], 0
	v_mfma_f32_16x16x32_bf16 v[82:85], v[228:231], v[10:13], 0
	s_waitcnt lgkmcnt(4)
	v_mfma_f32_16x16x32_bf16 v[110:113], v[232:235], v[2:5], 0
	v_mfma_f32_16x16x32_bf16 v[86:89], v[232:235], v[10:13], 0
	s_waitcnt lgkmcnt(3)
	v_mfma_f32_16x16x32_bf16 v[98:101], v[236:239], v[6:9], v[98:101]
	v_mfma_f32_16x16x32_bf16 v[90:93], v[236:239], v[14:17], v[90:93]
	s_waitcnt lgkmcnt(2)
	v_mfma_f32_16x16x32_bf16 v[106:109], v[240:243], v[6:9], v[106:109]
	v_mfma_f32_16x16x32_bf16 v[94:97], v[240:243], v[14:17], v[94:97]
	s_waitcnt lgkmcnt(1)
	v_mfma_f32_16x16x32_bf16 v[102:105], v[244:247], v[6:9], v[102:105]
	v_mfma_f32_16x16x32_bf16 v[82:85], v[244:247], v[14:17], v[82:85]
	s_waitcnt lgkmcnt(0)
	v_mfma_f32_16x16x32_bf16 v[110:113], v[198:201], v[6:9], v[110:113]
	v_mfma_f32_16x16x32_bf16 v[86:89], v[198:201], v[14:17], v[86:89]
	ds_read_b64 v[220:221], v207 offset:8192
	ds_read_b64 v[222:223], v208 offset:8192
	ds_read_b64 v[224:225], v209 offset:8192
	ds_read_b64 v[226:227], v210 offset:8192
	ds_read_b64 v[228:229], v207 offset:10240
	ds_read_b64 v[230:231], v208 offset:10240
	ds_read_b64 v[232:233], v209 offset:10240
	ds_read_b64 v[234:235], v210 offset:10240
	ds_read_b64 v[236:237], v207 offset:12288
	ds_read_b64 v[238:239], v208 offset:12288
	ds_read_b64 v[240:241], v209 offset:12288
	ds_read_b64 v[242:243], v210 offset:12288
	ds_read_b64 v[244:245], v211 offset:8192
	ds_read_b64 v[246:247], v212 offset:8192
	ds_read_b64 v[198:199], v213 offset:8192
	ds_read_b64 v[200:201], v214 offset:8192
	s_cbranch_scc1 .LBB0_673
	v_fmamk_f32 v74, v98, 0x3fb8aa3b, v205
	v_fmamk_f32 v75, v99, 0x3fb8aa3b, v205
	v_fmamk_f32 v76, v100, 0x3fb8aa3b, v205
	v_fmamk_f32 v77, v101, 0x3fb8aa3b, v205
	v_fmamk_f32 v78, v106, 0x3fb8aa3b, v205
	v_fmamk_f32 v79, v107, 0x3fb8aa3b, v205
	v_fmamk_f32 v80, v108, 0x3fb8aa3b, v205
	v_fmamk_f32 v81, v109, 0x3fb8aa3b, v205
	v_fmamk_f32 v164, v102, 0x3fb8aa3b, v205
	v_fmamk_f32 v165, v103, 0x3fb8aa3b, v205
	v_fmamk_f32 v166, v104, 0x3fb8aa3b, v205
	v_fmamk_f32 v167, v105, 0x3fb8aa3b, v205
	v_fmamk_f32 v168, v110, 0x3fb8aa3b, v205
	v_fmamk_f32 v169, v111, 0x3fb8aa3b, v205
	v_fmamk_f32 v170, v112, 0x3fb8aa3b, v205
	v_fmamk_f32 v171, v113, 0x3fb8aa3b, v205
	v_exp_f32_e32 v74, v74
	v_exp_f32_e32 v75, v75
	v_exp_f32_e32 v76, v76
	v_exp_f32_e32 v77, v77
	v_exp_f32_e32 v78, v78
	v_exp_f32_e32 v79, v79
	v_exp_f32_e32 v80, v80
	v_exp_f32_e32 v81, v81
	v_exp_f32_e32 v164, v164
	v_exp_f32_e32 v165, v165
	v_exp_f32_e32 v166, v166
	v_exp_f32_e32 v167, v167
	v_exp_f32_e32 v168, v168
	v_exp_f32_e32 v169, v169
	v_exp_f32_e32 v170, v170
	v_exp_f32_e32 v171, v171
	v_cmp_gt_i32_e32 vcc, v118, v215
	v_cmp_lt_i32_e64 s[2:3], v118, v215
	v_cmp_gt_i32_e64 s[52:53], v119, v215
	v_cmp_gt_i32_e64 s[54:55], v192, v215
	v_cmp_gt_i32_e64 s[40:41], v120, v215
	v_cmp_gt_i32_e64 s[42:43], v193, v215
	v_cmp_gt_i32_e64 s[56:57], v122, v215
	v_cmp_gt_i32_e64 s[58:59], v121, v215
	v_cmp_gt_i32_e64 s[44:45], v194, v215
	v_cmp_gt_i32_e64 s[46:47], v195, v215
	v_cmp_gt_i32_e64 s[60:61], v206, v215
	v_cmp_gt_i32_e64 s[62:63], v124, v215
	v_cmp_gt_i32_e64 s[48:49], v126, v215
	v_cmp_gt_i32_e64 s[50:51], v123, v215
	v_cmp_gt_i32_e64 s[64:65], v125, v215
	v_cmp_gt_i32_e64 s[66:67], v127, v215
	v_cndmask_b32_e64 v74, v74, 0, vcc
	v_cndmask_b32_e64 v75, 0, v75, s[2:3]
	v_cndmask_b32_e64 v76, v76, 0, s[52:53]
	v_cndmask_b32_e64 v77, v77, 0, s[54:55]
	v_cndmask_b32_e64 v78, v78, 0, s[40:41]
	v_cndmask_b32_e64 v79, v79, 0, s[42:43]
	v_cndmask_b32_e64 v80, v80, 0, s[56:57]
	v_cndmask_b32_e64 v81, v81, 0, s[58:59]
	v_cndmask_b32_e64 v164, v164, 0, s[44:45]
	v_cndmask_b32_e64 v165, v165, 0, s[46:47]
	v_cndmask_b32_e64 v166, v166, 0, s[60:61]
	v_cndmask_b32_e64 v167, v167, 0, s[62:63]
	v_cndmask_b32_e64 v168, v168, 0, s[48:49]
	v_cndmask_b32_e64 v169, v169, 0, s[50:51]
	v_cndmask_b32_e64 v170, v170, 0, s[64:65]
	v_cndmask_b32_e64 v171, v171, 0, s[66:67]
	v_cvt_pk_bf16_f32 v74, v74, v75
	v_cvt_pk_bf16_f32 v75, v76, v77
	v_cvt_pk_bf16_f32 v76, v78, v79
	v_cvt_pk_bf16_f32 v77, v80, v81
	v_cvt_pk_bf16_f32 v78, v164, v165
	v_cvt_pk_bf16_f32 v79, v166, v167
	v_cvt_pk_bf16_f32 v80, v168, v169
	v_cvt_pk_bf16_f32 v81, v170, v171
	v_fmamk_f32 v164, v90, 0x3fb8aa3b, v205
	v_fmamk_f32 v165, v91, 0x3fb8aa3b, v205
	v_fmamk_f32 v166, v92, 0x3fb8aa3b, v205
	v_fmamk_f32 v167, v93, 0x3fb8aa3b, v205
	v_fmamk_f32 v168, v94, 0x3fb8aa3b, v205
	v_fmamk_f32 v169, v95, 0x3fb8aa3b, v205
	v_fmamk_f32 v170, v96, 0x3fb8aa3b, v205
	v_fmamk_f32 v171, v97, 0x3fb8aa3b, v205
	v_fmamk_f32 v172, v82, 0x3fb8aa3b, v205
	v_fmamk_f32 v173, v83, 0x3fb8aa3b, v205
	v_fmamk_f32 v174, v84, 0x3fb8aa3b, v205
	v_fmamk_f32 v175, v85, 0x3fb8aa3b, v205
	v_fmamk_f32 v176, v86, 0x3fb8aa3b, v205
	v_fmamk_f32 v177, v87, 0x3fb8aa3b, v205
	v_fmamk_f32 v178, v88, 0x3fb8aa3b, v205
	v_fmamk_f32 v179, v89, 0x3fb8aa3b, v205
	v_exp_f32_e32 v164, v164
	v_exp_f32_e32 v165, v165
	v_exp_f32_e32 v166, v166
	v_exp_f32_e32 v167, v167
	v_exp_f32_e32 v168, v168
	v_exp_f32_e32 v169, v169
	v_exp_f32_e32 v170, v170
	v_exp_f32_e32 v171, v171
	v_exp_f32_e32 v172, v172
	v_exp_f32_e32 v173, v173
	v_exp_f32_e32 v174, v174
	v_exp_f32_e32 v175, v175
	v_exp_f32_e32 v176, v176
	v_exp_f32_e32 v177, v177
	v_exp_f32_e32 v178, v178
	v_exp_f32_e32 v179, v179
	v_cndmask_b32_e64 v164, v164, 0, vcc
	v_cndmask_b32_e64 v165, 0, v165, s[2:3]
	v_cndmask_b32_e64 v166, v166, 0, s[52:53]
	v_cndmask_b32_e64 v167, v167, 0, s[54:55]
	v_cndmask_b32_e64 v168, v168, 0, s[40:41]
	v_cndmask_b32_e64 v169, v169, 0, s[42:43]
	v_cndmask_b32_e64 v170, v170, 0, s[56:57]
	v_cndmask_b32_e64 v171, v171, 0, s[58:59]
	v_cndmask_b32_e64 v172, v172, 0, s[44:45]
	v_cndmask_b32_e64 v173, v173, 0, s[46:47]
	v_cndmask_b32_e64 v174, v174, 0, s[60:61]
	v_cndmask_b32_e64 v175, v175, 0, s[62:63]
	v_cndmask_b32_e64 v176, v176, 0, s[48:49]
	v_cndmask_b32_e64 v177, v177, 0, s[50:51]
	v_cndmask_b32_e64 v178, v178, 0, s[64:65]
	v_cndmask_b32_e64 v179, v179, 0, s[66:67]
	s_mov_b64 s[2:3], 0
